# XCD barrier leader publishes the per-XCD generation word before its own L1 invalidate
# speedup vs baseline: 1.0018x; 1.0018x over previous
; DEV unsigned xb_ld(unsigned* p) { return __hip_atomic_load(p, __ATOMIC_RELAXED, __HIP_MEMORY_SCOPE_AGENT); }
; DEV unsigned xb_add(unsigned* p, unsigned v) { return __hip_atomic_fetch_add(p, v, __ATOMIC_RELAXED, __HIP_MEMORY_SCOPE_AGENT); }
; #define XB_SPIN(cond, bar) do { unsigned _sp = 0; while (cond) { __builtin_amdgcn_s_sleep(1); \
;     if ((++_sp & 255u) == 0u) { if (xb_ld(&(bar)[XB_TMO])) break; if (_sp > XB_SPIN_CAP) { atomicAdd(&(bar)[XB_TMO], 1u); break; } } } } while (0)
; DEV void xcd_barrier(unsigned* bar, unsigned x, volatile LAS unsigned* st) {
;     ...
;     const unsigned old = xb_add(&bar[XB_XSUB(x)], 1u);
;     const unsigned gen = old / nloc;
;     if (old + 1u == (gen + 1u) * nloc) {
;       __builtin_amdgcn_fence(__ATOMIC_RELEASE, "agent");
;       asm volatile("s_waitcnt vmcnt(0)" ::: "memory");
;       const unsigned og = xb_add(&bar[XB_TOP], 1u);
;       const unsigned tg = og / nx;
;       if (og + 1u == (tg + 1u) * nx) xb_add(&bar[XB_TOPGEN], 1u);
;       else XB_SPIN(xb_ld(&bar[XB_TOPGEN]) == tg, bar);
;       __builtin_amdgcn_fence(__ATOMIC_ACQUIRE, "agent");
;       xb_add(&bar[XB_XGEN(x)], 1u);
;       asm volatile("s_waitcnt vmcnt(0)" ::: "memory");
;     } else {
;       XB_SPIN(xb_ld(&bar[XB_XGEN(x)]) == gen, bar);
;       __builtin_amdgcn_fence(__ATOMIC_ACQUIRE, "agent");
;       asm volatile("s_waitcnt vmcnt(0)" ::: "memory");
.LBB0_597:
	s_or_b64 exec, exec, s[2:3]
	s_mov_b64 s[2:3], exec
	v_mbcnt_lo_u32_b32 v0, s2, 0
	v_mbcnt_hi_u32_b32 v0, s3, v0
	v_cmp_eq_u32_e32 vcc, 0, v0
	s_waitcnt vmcnt(0)
	s_and_saveexec_b64 s[4:5], vcc
	s_cbranch_execz .LBB0_599
	s_bcnt1_i32_b64 s2, s[2:3]
	v_mov_b32_e32 v0, s2
	v_readlane_b32 s2, v241, 45
	v_readlane_b32 s3, v241, 46
	s_nop 4
	global_atomic_add v145, v0, s[2:3]
.LBB0_599:
	s_or_b64 exec, exec, s[4:5]
	buffer_inv sc1
	s_waitcnt vmcnt(0)
